# MoBA: T5-bias gather (position reads, clamp, LUT lookups) issued between the QK MFMAs; logits accumulate from 0 and the static softmax shift is added with the bias afterwards
# speedup vs baseline: 1.0004x; 1.0004x over previous
; template <int DQK, bool MOBA>
; __device__ __forceinline__ void attn_unit(const Args& A, int b, int h, int qb, lptr lds) {
;     ...
;         negm = -(sqrtf(qss * (128.0f * gmx * gmx + 64.0f * grx * grx)) * 1.01f + bmx + 0.01f);
;     }
;     const int NT = 4 * (own + 1);
;     u32x4 kr0, kr1, kr2, vr0, vr1; int pkr = 0;
;     kr2 = (u32x4){0u, 0u, 0u, 0u};
;     ...
;     f32x16 o[4];
; #pragma unroll
;     for (int d = 0; d < 4; ++d)
; #pragma unroll
;         for (int r = 0; r < 16; ++r) o[d][r] = 0.f;
;     float lrow = 0.f;
;     ATT_LOAD(0); ATT_WRITE(0);
;     if (NT > 1) ATT_LOAD(1);
;     __syncthreads();
.LBB0_779:
	s_or_b64 exec, exec, s[0:1]
	s_waitcnt lgkmcnt(5)
	v_max_f32_e32 v1, v21, v21
	v_max_f32_e32 v2, v19, v19
	v_max_f32_e32 v1, v2, v1
	v_mul_f32_e32 v3, 0x43000000, v1
	v_add_f32_e32 v0, v16, v17
	v_fma_f32 v1, v1, v3, 0
	v_mul_f32_e32 v0, v0, v1
	v_mul_f32_e32 v1, 0x4f800000, v0
	v_cmp_gt_f32_e32 vcc, s35, v0
	s_waitcnt lgkmcnt(4)
	v_max_f32_e32 v2, v20, v20
	v_max_f32_e32 v3, v18, v18
	v_cndmask_b32_e32 v0, v0, v1, vcc
	v_sqrt_f32_e32 v1, v0
	v_max_f32_e32 v2, v3, v2
	s_lshl_b32 s18, s18, 2
	s_add_i32 s19, s18, 4
	v_add_u32_e32 v3, -1, v1
	v_fma_f32 v4, -v3, v1, v0
	v_cmp_ge_f32_e64 s[0:1], 0, v4
	v_add_u32_e32 v4, 1, v1
	v_lshlrev_b32_e32 v176, 2, v82
	v_cndmask_b32_e64 v3, v1, v3, s[0:1]
	v_fma_f32 v1, -v4, v1, v0
	v_cmp_lt_f32_e64 s[0:1], 0, v1
	v_mov_b32_e32 v48, v181
	v_mov_b32_e32 v49, v181
	v_cndmask_b32_e64 v1, v3, v4, s[0:1]
	v_mul_f32_e32 v3, 0x37800000, v1
	v_cndmask_b32_e32 v1, v1, v3, vcc
	v_cmp_class_f32_e32 vcc, v0, v205
	s_add_i32 s0, 0, 0x12800
	v_lshlrev_b32_e32 v3, 3, v162
	v_cndmask_b32_e32 v0, v1, v0, vcc
	v_mul_u32_u24_e32 v1, 0x110, v83
	v_fmac_f32_e32 v2, 0x3f8147ae, v0
	v_add3_u32 v179, 0, v1, v36
	v_lshrrev_b32_e32 v1, 2, v162
	v_add_f32_e32 v0, 0x3c23d70a, v2
	v_and_or_b32 v1, v1, 3, v176
	v_lshlrev_b32_e32 v2, 1, v162
	s_add_u32 s20, s95, s4
	v_mad_u32_u24 v1, v1, s12, 0
	v_and_b32_e32 v2, 32, v2
	v_and_b32_e32 v3, 24, v3
	s_addc_u32 s21, s8, s5
	v_mul_lo_u32 v174, v22, s12
	v_add3_u32 v183, v1, v2, v3
	v_xor_b32_e32 v64, 0x80000000, v0
	v_mov_b32_e32 v231, v64
	v_bfi_b32 v115, s14, v37, v37
	s_add_u32 s22, s9, s4
	v_add_u32_e32 v185, s0, v36
	v_mov_b32_e32 v50, v181
	v_mov_b32_e32 v51, v181
	v_mov_b32_e32 v52, v181
	v_mov_b32_e32 v53, v181
	v_mov_b32_e32 v54, v181
	v_mov_b32_e32 v55, v181
	v_mov_b32_e32 v56, v181
	v_mov_b32_e32 v57, v181
	v_mov_b32_e32 v58, v181
	v_mov_b32_e32 v59, v181
	v_mov_b32_e32 v60, v181
	v_mov_b32_e32 v61, v181
	v_mov_b32_e32 v62, v181
	v_mov_b32_e32 v63, v181
	v_mov_b64_e32 v[32:33], v[48:49]
	v_mov_b64_e32 v[16:17], v[48:49]
	v_mov_b64_e32 v[0:1], v[48:49]
	v_add_u32_e32 v163, 0x2200, v167
	v_add_u32_e32 v175, 0x2800, v174
	s_mov_b32 s13, 0
	s_mov_b32 s15, 2
	v_or_b32_e32 v177, s71, v83
	v_lshl_add_u32 v178, v162, 2, s0
	v_mov_b32_e32 v65, v64
	v_mov_b32_e32 v66, v64
	v_mov_b32_e32 v67, v64
	v_mov_b32_e32 v68, v64
	v_mov_b32_e32 v69, v64
	v_mov_b32_e32 v70, v64
	v_mov_b32_e32 v71, v64
	v_mov_b32_e32 v72, v64
	v_mov_b32_e32 v73, v64
	v_mov_b32_e32 v74, v64
	v_mov_b32_e32 v75, v64
	v_mov_b32_e32 v76, v64
	v_mov_b32_e32 v77, v64
	v_mov_b32_e32 v78, v64
	v_mov_b32_e32 v79, v64
	v_bfi_b32 v119, s14, v84, v84
	v_bfi_b32 v123, s14, v80, v80
	v_bfi_b32 v127, s14, v81, v81
	v_bfi_b32 v131, s14, v85, v85
	v_bfi_b32 v135, s14, v86, v86
	v_bfi_b32 v139, s14, v87, v87
	v_bfi_b32 v143, s14, v88, v88
	s_addc_u32 s23, s10, s5
	s_addk_i32 s17, 0x100
	v_mov_b32_e32 v184, 0
	v_mov_b64_e32 v[34:35], v[50:51]
	v_mov_b64_e32 v[36:37], v[52:53]
	v_mov_b64_e32 v[38:39], v[54:55]
	v_mov_b64_e32 v[40:41], v[56:57]
	v_mov_b64_e32 v[42:43], v[58:59]
	v_mov_b64_e32 v[44:45], v[60:61]
	v_mov_b64_e32 v[46:47], v[62:63]
	v_mov_b64_e32 v[18:19], v[50:51]
	v_mov_b64_e32 v[20:21], v[52:53]
	v_mov_b64_e32 v[22:23], v[54:55]
	v_mov_b64_e32 v[24:25], v[56:57]
	v_mov_b64_e32 v[26:27], v[58:59]
	v_mov_b64_e32 v[28:29], v[60:61]
	v_mov_b64_e32 v[30:31], v[62:63]
	v_mov_b64_e32 v[2:3], v[50:51]
	v_mov_b64_e32 v[4:5], v[52:53]
	v_mov_b64_e32 v[6:7], v[54:55]
	v_mov_b64_e32 v[8:9], v[56:57]
	v_mov_b64_e32 v[10:11], v[58:59]
	v_mov_b64_e32 v[12:13], v[60:61]
	v_mov_b64_e32 v[14:15], v[62:63]
	s_waitcnt lgkmcnt(0)
	s_barrier
	s_branch .LBB0_782

; #define LAS __attribute__((address_space(3)))
; #define MFMA32(a, b, c) __builtin_amdgcn_mfma_f32_32x32x16_bf16((a), (b), (c), 0, 0, 0)
; template <int DQK, bool MOBA>
; __device__ __forceinline__ void attn_unit(const Args& A, int b, int h, int qb, lptr lds) {
;     ...
;             lptr kb = lds + L::OFF_K + buf * L::KBUF + r32 * L::KROW + 16 * hi;
;             f32x16 s0, s1;
; #pragma unroll
;             for (int r = 0; r < 16; ++r) { s0[r] = negm; s1[r] = negm; }
;             {
;                 bf16x8 ka[2][2], kc[2][2];
; #pragma unroll
;                 for (int i = 0; i < 2; ++i) { ka[0][i] = *(const LAS bf16x8*)(kb + 32 * i); kc[0][i] = *(const LAS bf16x8*)(kb + 32 * L::KROW + 32 * i); }
;                 __builtin_amdgcn_sched_barrier(0);
; #pragma unroll
;                 for (int sb = 0; sb < NS; sb += 2) {
;                     const int cur = (sb >> 1) & 1, nxt = cur ^ 1;
;                     if (sb + 2 < NS) {
; #pragma unroll
;                         for (int i = 0; i < 2; ++i) { ka[nxt][i] = *(const LAS bf16x8*)(kb + 32 * (sb + 2 + i)); kc[nxt][i] = *(const LAS bf16x8*)(kb + 32 * L::KROW + 32 * (sb + 2 + i)); }
;                     }
;                     __builtin_amdgcn_sched_barrier(0);
; #pragma unroll
;                     for (int i = 0; i < 2; ++i) { s0 = MFMA32(ka[cur][i], qf[sb + i], s0); s1 = MFMA32(kc[cur][i], qf[sb + i], s1); }
;                     __builtin_amdgcn_sched_barrier(0);
;                 }
;             }
;             if (MOBA) {
;                 const LAS int* pp = (const LAS int*)(lds + L::OFF_POS + buf * 256);
; #pragma unroll
;                 for (int a = 0; a < 4; ++a) {
;                     const i32x4 p0 = *(const LAS i32x4*)(pp + 8 * a + 4 * hi), p1 = *(const LAS i32x4*)(pp + 32 + 8 * a + 4 * hi);
;                     const int pa[4] = {p0.x, p0.y, p0.z, p0.w}, pb[4] = {p1.x, p1.y, p1.z, p1.w};
; #pragma unroll
;                     for (int e = 0; e < 4; ++e) {
;                         int d0 = pq - pa[e]; d0 = d0 < 0 ? 0 : (d0 > 1023 ? 1023 : d0);
;                         int d1 = pq - pb[e]; d1 = d1 < 0 ? 0 : (d1 > 1023 ? 1023 : d1);
;                         s0[4 * a + e] += lut[d0]; s1[4 * a + e] += lut[d1];
.LBB0_794:
	s_mul_i32 s6, s24, 0x4400
	v_lshl_add_u32 v226, s24, 8, v185
	v_add_u32_e32 v203, s6, v179
	ds_read_b128 v[64:67], v226
	ds_read_b128 v[68:71], v226 offset:32
	ds_read_b128 v[72:75], v226 offset:64
	ds_read_b128 v[76:79], v226 offset:96
	ds_read_b128 v[236:239], v226 offset:128
	ds_read_b128 v[240:243], v226 offset:160
	ds_read_b128 v[244:247], v226 offset:192
	ds_read_b128 v[248:251], v226 offset:224
	ds_read_b128 v[80:83], v203
	ds_read_b128 v[186:189], v203 offset:32
	ds_read_b128 v[190:193], v203 offset:8704
	ds_read_b128 v[194:197], v203 offset:8736
	s_or_b64 s[42:43], s[4:5], s[0:1]
	ds_read_b128 v[198:201], v203 offset:64
	ds_read_b128 v[210:213], v203 offset:96
	ds_read_b128 v[214:217], v203 offset:8768
	ds_read_b128 v[218:221], v203 offset:8800
	s_mov_b64 vcc, s[42:43]
	s_mov_b32 s0, 0x12a00
	v_cndmask_b32_e32 v227, v229, v171, vcc
	v_cndmask_b32_e32 v228, v230, v208, vcc
	s_waitcnt lgkmcnt(7)
	v_mfma_f32_32x32x16_bf16 v[96:111], v[80:83], v[112:115], 0
	v_sub_u32_e32 v64, v227, v64
	v_sub_u32_e32 v65, v227, v65
	v_sub_u32_e32 v66, v227, v66
	v_sub_u32_e32 v67, v227, v67
	v_med3_i32 v64, v64, s0, v228
	v_med3_i32 v65, v65, s0, v228
	v_med3_i32 v66, v66, s0, v228
	v_med3_i32 v67, v67, s0, v228
	ds_read_b32 v64, v64
	ds_read_b32 v65, v65
	ds_read_b32 v66, v66
	ds_read_b32 v67, v67
	s_waitcnt lgkmcnt(5)
	v_mfma_f32_32x32x16_bf16 v[80:95], v[190:193], v[112:115], 0
	v_sub_u32_e32 v68, v227, v68
	v_sub_u32_e32 v69, v227, v69
	v_sub_u32_e32 v70, v227, v70
	v_sub_u32_e32 v71, v227, v71
	v_med3_i32 v68, v68, s0, v228
	v_med3_i32 v69, v69, s0, v228
	v_med3_i32 v70, v70, s0, v228
	v_med3_i32 v71, v71, s0, v228
	ds_read_b32 v68, v68
	ds_read_b32 v69, v69
	ds_read_b32 v70, v70
	ds_read_b32 v71, v71
	v_mfma_f32_32x32x16_bf16 v[96:111], v[186:189], v[116:119], v[96:111]
	v_sub_u32_e32 v72, v227, v72
	v_sub_u32_e32 v73, v227, v73
	v_sub_u32_e32 v74, v227, v74
	v_sub_u32_e32 v75, v227, v75
	v_med3_i32 v72, v72, s0, v228
	v_med3_i32 v73, v73, s0, v228
	v_med3_i32 v74, v74, s0, v228
	v_med3_i32 v75, v75, s0, v228
	ds_read_b32 v72, v72
	ds_read_b32 v73, v73
	ds_read_b32 v74, v74
	ds_read_b32 v75, v75
	s_waitcnt lgkmcnt(4)
	v_mfma_f32_32x32x16_bf16 v[80:95], v[194:197], v[116:119], v[80:95]
	v_sub_u32_e32 v76, v227, v76
	v_sub_u32_e32 v77, v227, v77
	v_sub_u32_e32 v78, v227, v78
	v_sub_u32_e32 v79, v227, v79
	v_med3_i32 v76, v76, s0, v228
	v_med3_i32 v77, v77, s0, v228
	v_med3_i32 v78, v78, s0, v228
	v_med3_i32 v79, v79, s0, v228
	ds_read_b32 v76, v76
	ds_read_b32 v77, v77
	ds_read_b32 v78, v78
	ds_read_b32 v79, v79
	ds_read_b128 v[186:189], v203 offset:128
	ds_read_b128 v[190:193], v203 offset:160
	ds_read_b128 v[194:197], v203 offset:8832
	ds_read_b128 v[222:225], v203 offset:8864
	s_waitcnt lgkmcnt(7)
	v_mfma_f32_32x32x16_bf16 v[96:111], v[198:201], v[120:123], v[96:111]
	v_sub_u32_e32 v236, v227, v236
	v_sub_u32_e32 v237, v227, v237
	v_sub_u32_e32 v238, v227, v238
	v_sub_u32_e32 v239, v227, v239
	v_med3_i32 v236, v236, s0, v228
	v_med3_i32 v237, v237, s0, v228
	v_med3_i32 v238, v238, s0, v228
	v_med3_i32 v239, v239, s0, v228
	ds_read_b32 v236, v236
	ds_read_b32 v237, v237
	ds_read_b32 v238, v238
	ds_read_b32 v239, v239
	s_waitcnt lgkmcnt(5)
	v_mfma_f32_32x32x16_bf16 v[80:95], v[214:217], v[120:123], v[80:95]
	v_sub_u32_e32 v240, v227, v240
	v_sub_u32_e32 v241, v227, v241
	v_sub_u32_e32 v242, v227, v242
	v_sub_u32_e32 v243, v227, v243
	v_med3_i32 v240, v240, s0, v228
	v_med3_i32 v241, v241, s0, v228
	v_med3_i32 v242, v242, s0, v228
	v_med3_i32 v243, v243, s0, v228
	ds_read_b32 v240, v240
	ds_read_b32 v241, v241
	ds_read_b32 v242, v242
	ds_read_b32 v243, v243
	v_mfma_f32_32x32x16_bf16 v[96:111], v[210:213], v[124:127], v[96:111]
	v_sub_u32_e32 v244, v227, v244
	v_sub_u32_e32 v245, v227, v245
	v_sub_u32_e32 v246, v227, v246
	v_sub_u32_e32 v247, v227, v247
	v_med3_i32 v244, v244, s0, v228
	v_med3_i32 v245, v245, s0, v228
	v_med3_i32 v246, v246, s0, v228
	v_med3_i32 v247, v247, s0, v228
	ds_read_b32 v244, v244
	ds_read_b32 v245, v245
	ds_read_b32 v246, v246
	ds_read_b32 v247, v247
	s_waitcnt lgkmcnt(4)
	v_mfma_f32_32x32x16_bf16 v[80:95], v[218:221], v[124:127], v[80:95]
	v_sub_u32_e32 v248, v227, v248
	v_sub_u32_e32 v249, v227, v249
	v_sub_u32_e32 v250, v227, v250
	v_sub_u32_e32 v251, v227, v251
	v_med3_i32 v248, v248, s0, v228
	v_med3_i32 v249, v249, s0, v228
	v_med3_i32 v250, v250, s0, v228
	v_med3_i32 v251, v251, s0, v228
	ds_read_b32 v248, v248
	ds_read_b32 v249, v249
	ds_read_b32 v250, v250
	ds_read_b32 v251, v251
	ds_read_b128 v[198:201], v203 offset:192
	ds_read_b128 v[210:213], v203 offset:224
	ds_read_b128 v[214:217], v203 offset:8896
	ds_read_b128 v[218:221], v203 offset:8928
	s_waitcnt lgkmcnt(7)
	v_mfma_f32_32x32x16_bf16 v[96:111], v[186:189], v[128:131], v[96:111]
	s_waitcnt lgkmcnt(5)
	v_mfma_f32_32x32x16_bf16 v[80:95], v[194:197], v[128:131], v[80:95]
	v_mfma_f32_32x32x16_bf16 v[96:111], v[190:193], v[132:135], v[96:111]
	s_waitcnt lgkmcnt(4)
	v_mfma_f32_32x32x16_bf16 v[80:95], v[222:225], v[132:135], v[80:95]
	s_waitcnt lgkmcnt(3)
	v_mfma_f32_32x32x16_bf16 v[96:111], v[198:201], v[136:139], v[96:111]
	s_waitcnt lgkmcnt(1)
	v_mfma_f32_32x32x16_bf16 v[80:95], v[214:217], v[136:139], v[80:95]
	v_mfma_f32_32x32x16_bf16 v[96:111], v[210:213], v[140:143], v[96:111]
	s_waitcnt lgkmcnt(0)
; #define LAS __attribute__((address_space(3)))
; template <int DQK, bool MOBA>
; __device__ __forceinline__ void attn_unit(const Args& A, int b, int h, int qb, lptr lds) {
;     ...
;             if (MOBA) {
;                 const LAS int* pp = (const LAS int*)(lds + L::OFF_POS + buf * 256);
; #pragma unroll
;                 for (int a = 0; a < 4; ++a) {
;                     const i32x4 p0 = *(const LAS i32x4*)(pp + 8 * a + 4 * hi), p1 = *(const LAS i32x4*)(pp + 32 + 8 * a + 4 * hi);
;                     const int pa[4] = {p0.x, p0.y, p0.z, p0.w}, pb[4] = {p1.x, p1.y, p1.z, p1.w};
; #pragma unroll
;                     for (int e = 0; e < 4; ++e) {
;                         int d0 = pq - pa[e]; d0 = d0 < 0 ? 0 : (d0 > 1023 ? 1023 : d0);
;                         int d1 = pq - pb[e]; d1 = d1 < 0 ? 0 : (d1 > 1023 ? 1023 : d1);
;                         s0[4 * a + e] += lut[d0]; s1[4 * a + e] += lut[d1];
;                     }
;                 }
;                 if (!lsel) {
; #pragma unroll
;                     for (int r = 0; r < 16; ++r) { s0[r] = NEG; s1[r] = NEG; }
;                 }
;             }
;             if (diag) {
; #pragma unroll
;                 for (int r = 0; r < 16; ++r) {
;                     const int kl = 64 * tt + (r & 3) + 8 * (r >> 2) + 4 * hi;
;                     if (kl > qrel) s0[r] = NEG;
;                     if (kl + 32 > qrel) s1[r] = NEG;
;                 }
	v_mfma_f32_32x32x16_bf16 v[80:95], v[218:221], v[140:143], v[80:95]
	v_add_f32_e32 v64, v64, v231
	v_add_f32_e32 v65, v65, v231
	v_add_f32_e32 v66, v66, v231
	v_add_f32_e32 v67, v67, v231
	v_add_f32_e32 v68, v68, v231
	v_add_f32_e32 v69, v69, v231
	v_add_f32_e32 v70, v70, v231
	v_add_f32_e32 v71, v71, v231
	v_add_f32_e32 v72, v72, v231
	v_add_f32_e32 v73, v73, v231
	v_add_f32_e32 v74, v74, v231
	v_add_f32_e32 v75, v75, v231
	v_add_f32_e32 v76, v76, v231
	v_add_f32_e32 v77, v77, v231
	v_add_f32_e32 v78, v78, v231
	v_add_f32_e32 v79, v79, v231
	v_add_f32_e32 v236, v236, v231
	v_add_f32_e32 v237, v237, v231
	v_add_f32_e32 v238, v238, v231
	v_add_f32_e32 v239, v239, v231
	v_add_f32_e32 v240, v240, v231
	v_add_f32_e32 v241, v241, v231
	v_add_f32_e32 v242, v242, v231
	v_add_f32_e32 v243, v243, v231
	v_add_f32_e32 v244, v244, v231
	v_add_f32_e32 v245, v245, v231
	v_add_f32_e32 v246, v246, v231
	v_add_f32_e32 v247, v247, v231
	v_add_f32_e32 v248, v248, v231
	v_add_f32_e32 v249, v249, v231
	v_add_f32_e32 v250, v250, v231
	v_add_f32_e32 v251, v251, v231
	v_add_f32_e32 v90, v90, v246
	v_add_f32_e32 v236, v80, v236
	v_add_f32_e32 v80, v110, v78
	v_add_f32_e32 v237, v81, v237
	v_add_f32_e32 v81, v111, v79
	v_add_f32_e32 v238, v82, v238
	v_add_f32_e32 v82, v108, v76
	v_add_f32_e32 v239, v83, v239
	v_add_f32_e32 v83, v109, v77
	v_add_f32_e32 v240, v84, v240
	v_add_f32_e32 v84, v106, v74
	v_add_f32_e32 v106, v96, v64
	v_add_f32_e32 v96, v88, v244
	v_add_f32_e32 v88, v92, v248
	v_add_f32_e32 v92, v104, v72
	v_add_f32_e32 v104, v98, v66
	v_add_f32_e32 v98, v100, v68
	v_add_f32_e32 v100, v86, v242
	v_add_f32_e32 v86, v94, v250
	v_add_f32_e32 v94, v102, v70
	v_add_f32_e32 v241, v85, v241
	v_add_f32_e32 v85, v107, v75
	v_add_f32_e32 v107, v97, v65
	v_add_f32_e32 v97, v103, v71
	v_add_f32_e32 v243, v87, v243
	v_add_f32_e32 v87, v95, v251
	v_add_f32_e32 v95, v89, v245
	v_add_f32_e32 v89, v93, v249
	v_add_f32_e32 v93, v91, v247
	v_add_f32_e32 v91, v105, v73
	v_add_f32_e32 v105, v99, v67
	v_add_f32_e32 v99, v101, v69
	v_mov_b32_e32 v110, v236
	v_mov_b32_e32 v111, v237
	v_mov_b32_e32 v108, v238
	v_mov_b32_e32 v109, v239
	v_mov_b32_e32 v102, v240
	v_mov_b32_e32 v103, v241
	v_mov_b32_e32 v101, v243
	s_andn2_b64 vcc, exec, s[4:5]
	s_cbranch_vccnz .LBB0_780
	v_add_u32_e32 v186, s13, v176
	v_add_u32_e32 v187, 32, v186
	v_cmp_le_i32_e32 vcc, v186, v177
	v_cmp_le_i32_e64 s[0:1], v187, v177
	v_add_u32_e32 v187, 33, v186
	v_cndmask_b32_e32 v106, v209, v106, vcc
	v_cmp_le_i32_e32 vcc, v187, v177
	v_add_u32_e32 v187, 2, v186
	v_cndmask_b32_e64 v110, v209, v110, s[0:1]
	v_cndmask_b32_e32 v111, v209, v111, vcc
	v_cmp_le_i32_e32 vcc, v187, v177
	v_add_u32_e32 v187, 34, v186
	v_cmp_lt_i32_e64 s[0:1], v186, v177
	v_cndmask_b32_e32 v104, v209, v104, vcc
	v_cmp_le_i32_e32 vcc, v187, v177
	v_add_u32_e32 v187, 3, v186
	v_cndmask_b32_e64 v107, v209, v107, s[0:1]
	v_cndmask_b32_e32 v108, v209, v108, vcc
	v_cmp_le_i32_e32 vcc, v187, v177
	v_add_u32_e32 v187, 35, v186
	s_nop 0
	v_cndmask_b32_e32 v105, v209, v105, vcc
	v_cmp_le_i32_e32 vcc, v187, v177
	v_add_u32_e32 v187, 8, v186
	s_nop 0
	v_cndmask_b32_e32 v109, v209, v109, vcc
	v_cmp_le_i32_e32 vcc, v187, v177
	v_add_u32_e32 v187, 40, v186
	s_nop 0
	v_cndmask_b32_e32 v98, v209, v98, vcc
	v_cmp_le_i32_e32 vcc, v187, v177
	v_add_u32_e32 v187, 9, v186
	s_nop 0
	v_cndmask_b32_e32 v102, v209, v102, vcc
	v_cmp_le_i32_e32 vcc, v187, v177
	v_add_u32_e32 v187, 41, v186
	s_nop 0
	v_cndmask_b32_e32 v99, v209, v99, vcc
	v_cmp_le_i32_e32 vcc, v187, v177
	v_add_u32_e32 v187, 10, v186
	s_nop 0
	v_cndmask_b32_e32 v103, v209, v103, vcc
	v_cmp_le_i32_e32 vcc, v187, v177
	v_add_u32_e32 v187, 42, v186
	s_nop 0
	v_cndmask_b32_e32 v94, v209, v94, vcc
	v_cmp_le_i32_e32 vcc, v187, v177
	v_add_u32_e32 v187, 11, v186
	s_nop 0
	v_cndmask_b32_e32 v100, v209, v100, vcc
	v_cmp_le_i32_e32 vcc, v187, v177
	v_add_u32_e32 v187, 43, v186
	s_nop 0
	v_cndmask_b32_e32 v97, v209, v97, vcc
	v_cmp_le_i32_e32 vcc, v187, v177
	v_add_u32_e32 v187, 16, v186
	s_nop 0
	v_cndmask_b32_e32 v101, v209, v101, vcc
	v_cmp_le_i32_e32 vcc, v187, v177
	v_add_u32_e32 v187, 48, v186
	s_nop 0
	v_cndmask_b32_e32 v92, v209, v92, vcc
	v_cmp_le_i32_e32 vcc, v187, v177
	v_add_u32_e32 v187, 17, v186
	s_nop 0
	v_cndmask_b32_e32 v96, v209, v96, vcc
	v_cmp_le_i32_e32 vcc, v187, v177
	v_add_u32_e32 v187, 49, v186
	s_nop 0
	v_cndmask_b32_e32 v91, v209, v91, vcc
	v_cmp_le_i32_e32 vcc, v187, v177
	v_add_u32_e32 v187, 18, v186
	s_nop 0
	v_cndmask_b32_e32 v95, v209, v95, vcc
	v_cmp_le_i32_e32 vcc, v187, v177
	v_add_u32_e32 v187, 50, v186
	s_nop 0
	v_cndmask_b32_e32 v84, v209, v84, vcc
	v_cmp_le_i32_e32 vcc, v187, v177
	v_add_u32_e32 v187, 19, v186
	s_nop 0
	v_cndmask_b32_e32 v90, v209, v90, vcc
	v_cmp_le_i32_e32 vcc, v187, v177
	v_add_u32_e32 v187, 51, v186
	s_nop 0
	v_cndmask_b32_e32 v85, v209, v85, vcc
	v_cmp_le_i32_e32 vcc, v187, v177
	v_add_u32_e32 v187, 24, v186
	s_nop 0
	v_cndmask_b32_e32 v93, v209, v93, vcc
	v_cmp_le_i32_e32 vcc, v187, v177
	v_add_u32_e32 v187, 56, v186
	s_nop 0
	v_cndmask_b32_e32 v82, v209, v82, vcc
	v_cmp_le_i32_e32 vcc, v187, v177
	v_add_u32_e32 v187, 25, v186
	s_nop 0
	v_cndmask_b32_e32 v88, v209, v88, vcc
	v_cmp_le_i32_e32 vcc, v187, v177
	v_add_u32_e32 v187, 57, v186
	s_nop 0
	v_cndmask_b32_e32 v83, v209, v83, vcc
	v_cmp_le_i32_e32 vcc, v187, v177
	v_add_u32_e32 v187, 26, v186
	s_nop 0
	v_cndmask_b32_e32 v89, v209, v89, vcc
	v_cmp_le_i32_e32 vcc, v187, v177
	v_add_u32_e32 v187, 58, v186
	s_nop 0
	v_cndmask_b32_e32 v80, v209, v80, vcc
	v_cmp_le_i32_e32 vcc, v187, v177
	v_add_u32_e32 v187, 27, v186
	v_add_u32_e32 v186, 59, v186
	v_cndmask_b32_e32 v86, v209, v86, vcc
	v_cmp_le_i32_e32 vcc, v187, v177
	s_nop 1
	v_cndmask_b32_e32 v81, v209, v81, vcc
	v_cmp_le_i32_e32 vcc, v186, v177
	s_nop 1
	v_cndmask_b32_e32 v87, v209, v87, vcc
	s_branch .LBB0_780
